# XCD-parity workgroup partition (bid bit 0 instead of bit 3) for the P2 sub-phase order swap
# speedup vs baseline: 1.0017x; 1.0017x over previous
; #define LAS __attribute__((address_space(3)))
; __global__ void __launch_bounds__(512, 2) fwd_megakernel(Params p_) {
;     ...
;         if (PHM & 8)
;         {
;             TID_VARS
;             KARGS
;             { LAS float* WD0 = (LAS float*)lds; const float* wdw = p->in[I_WDW] + (size_t)l * 31 * 512;
;               for (int e = tid; e < 31 * 512; e += 512) WD0[e] = wdw[e]; }
.LBB0_291:
	s_or_b64 exec, exec, s[38:39]
	v_readlane_b32 s0, v253, 0
	v_mov_b32_e32 v48, v246
	v_readlane_b32 s1, v253, 1
	s_waitcnt lgkmcnt(0)
	s_barrier
	v_readlane_b32 s101, v253, 7
	s_nop 0
	s_bfe_u32 s101, s101, 0x10000
	s_movk_i32 s2, 0x3e00
	v_writelane_b32 v255, s0, 10
	s_load_dwordx2 s[6:7], s[0:1], 0xd0
	v_ashrrev_i32_e32 v49, 31, v48
	v_writelane_b32 v255, s1, 11
	v_readfirstlane_b32 s0, v48
	v_cmp_gt_i32_e32 vcc, s2, v48
	s_nop 0
	v_writelane_b32 v255, s0, 12
	s_and_saveexec_b64 s[8:9], vcc
	s_cbranch_execz .LBB0_306
	v_readlane_b32 s0, v255, 10
	v_readlane_b32 s1, v255, 11
	s_load_dwordx2 s[10:11], s[0:1], 0x68
	v_max_i32_e32 v0, 0x3c00, v48
	v_sub_u32_e32 v0, v0, v48
	v_add_u32_e32 v1, 0x1ff, v0
	s_movk_i32 s2, 0x1ff
	v_cmp_lt_u32_e32 vcc, s2, v1
	s_mov_b64 s[4:5], -1
	v_mov_b32_e32 v0, v48
	v_mov_b64_e32 v[2:3], v[48:49]
	s_and_saveexec_b64 s[12:13], vcc
	s_cbranch_execz .LBB0_303
	v_lshrrev_b32_e32 v2, 9, v1
	v_readlane_b32 s0, v255, 6
	s_mul_i32 s3, s0, 0xf800
	v_add_u32_e32 v4, -1, v2
	s_mul_hi_u32 s2, s0, 0xf800
	s_waitcnt lgkmcnt(0)
	s_add_u32 s14, s10, s3
	v_lshrrev_b32_e32 v3, 1, v4
	s_addc_u32 s15, s11, s2
	v_add_u32_e32 v1, 0x200, v48
	v_mov_b32_e32 v0, v48
	v_add_u32_e32 v3, 1, v3
	v_cmp_lt_u32_e32 vcc, 13, v4
	v_mov_b32_e32 v6, 0
	v_readlane_b32 s1, v255, 7
	s_and_saveexec_b64 s[16:17], vcc
	s_cbranch_execz .LBB0_297
	v_and_b32_e32 v4, -8, v3
	v_lshl_add_u32 v5, v48, 2, 0
	s_mov_b32 s2, 0
	s_mov_b64 s[18:19], 0
